# sample cumsum sequences also coalesced (32-element blocks via LDS transpose, 16 new elements scanned separately)
# speedup vs baseline: 1.0041x; 1.0041x over previous
.LBB0_362:
	s_and_b64 s[34:35], s[22:23], exec
	s_cselect_b32 s2, s20, s2
	s_ashr_i32 s38, s2, 3
	s_and_b32 s21, s2, 7
	s_and_b64 s[22:23], s[22:23], exec
	s_movk_i32 s2, 0x1000
	s_cselect_b32 s50, s2, 0x810
	s_add_i32 s2, s50, 63
	s_ashr_i32 s39, s38, 31
	v_readlane_b32 s52, v253, 0
	s_lshr_b32 s51, s2, 6
	s_lshl_b64 s[22:23], s[38:39], 9
	v_readlane_b32 s54, v253, 2
	v_readlane_b32 s53, v253, 1
	v_readlane_b32 s55, v253, 3
	v_readlane_b32 s56, v253, 4
	v_readlane_b32 s57, v253, 5
	v_readlane_b32 s58, v253, 6
	v_readlane_b32 s59, v253, 7
	s_add_u32 s22, s54, s22
	s_addc_u32 s23, s55, s23
	v_readlane_b32 s52, v253, 22
	s_lshl_b64 s[34:35], s[38:39], 16
	v_readlane_b32 s66, v253, 36
	v_readlane_b32 s67, v253, 37
	s_add_u32 s2, s66, s34
	s_addc_u32 s35, s67, s35
	s_lshl_b32 s40, s21, 2
	s_add_u32 s34, s2, s40
	s_addc_u32 s35, s35, 0
	s_lshl_b64 s[38:39], s[38:39], 17
	s_add_u32 s2, s47, s40
	s_addc_u32 s40, s48, 0
	v_mul_u32_u24_e32 v4, s51, v5
	s_add_u32 s38, s2, s38
	v_lshlrev_b32_e32 v2, 5, v4
	s_addc_u32 s39, s40, s39
	v_lshlrev_b32_e32 v17, 3, v4
	v_lshl_add_u64 v[6:7], s[38:39], 0, v[2:3]
	v_mov_b32_e32 v18, 0
	v_cndmask_b32_e64 v19, 0, 1, s[12:13]
	v_mov_b64_e32 v[8:9], v[6:7]
	v_mov_b32_e32 v2, v17
	v_mov_b32_e32 v20, v4
	s_mov_b32 s52, s51
	v_readlane_b32 s53, v253, 23
	v_readlane_b32 s54, v253, 24
	v_readlane_b32 s55, v253, 25
	v_readlane_b32 s56, v253, 26
	v_readlane_b32 s57, v253, 27
	v_readlane_b32 s58, v253, 28
	v_readlane_b32 s59, v253, 29
	v_readlane_b32 s60, v253, 30
	v_readlane_b32 s61, v253, 31
	v_readlane_b32 s62, v253, 32
	v_readlane_b32 s63, v253, 33
	v_readlane_b32 s64, v253, 34
	v_readlane_b32 s65, v253, 35
	s_cmp_gt_i32 s20, 31
	s_cbranch_scc1 .Lcs_sample
	v_readfirstlane_b32 s2, v227
	v_lshlrev_b32_e32 v22, 5, v5
	v_mov_b32_e32 v23, 0
	s_mov_b32 s40, 0x1000
	s_mov_b32 s41, 0
	s_lshr_b32 s2, s2, 6
	s_lshl_b32 s2, s2, 14
	v_lshl_add_u64 v[22:23], v[22:23], 0, s[38:39]
	global_load_dword v30, v[22:23], off
	global_load_dword v31, v[22:23], off offset:2048
	v_lshl_add_u64 v[22:23], v[22:23], 0, s[40:41]
	global_load_dword v32, v[22:23], off
	global_load_dword v33, v[22:23], off offset:2048
	v_lshl_add_u64 v[22:23], v[22:23], 0, s[40:41]
	global_load_dword v34, v[22:23], off
	global_load_dword v35, v[22:23], off offset:2048
	v_lshl_add_u64 v[22:23], v[22:23], 0, s[40:41]
	global_load_dword v36, v[22:23], off
	global_load_dword v37, v[22:23], off offset:2048
	v_lshl_add_u64 v[22:23], v[22:23], 0, s[40:41]
	global_load_dword v38, v[22:23], off
	global_load_dword v39, v[22:23], off offset:2048
	v_lshl_add_u64 v[22:23], v[22:23], 0, s[40:41]
	global_load_dword v40, v[22:23], off
	global_load_dword v41, v[22:23], off offset:2048
	v_lshl_add_u64 v[22:23], v[22:23], 0, s[40:41]
	global_load_dword v42, v[22:23], off
	global_load_dword v43, v[22:23], off offset:2048
	v_lshl_add_u64 v[22:23], v[22:23], 0, s[40:41]
	global_load_dword v44, v[22:23], off
	global_load_dword v45, v[22:23], off offset:2048
	v_lshl_add_u64 v[22:23], v[22:23], 0, s[40:41]
	global_load_dword v46, v[22:23], off
	global_load_dword v47, v[22:23], off offset:2048
	v_lshl_add_u64 v[22:23], v[22:23], 0, s[40:41]
	global_load_dword v48, v[22:23], off
	global_load_dword v49, v[22:23], off offset:2048
	v_lshl_add_u64 v[22:23], v[22:23], 0, s[40:41]
	global_load_dword v50, v[22:23], off
	global_load_dword v51, v[22:23], off offset:2048
	v_lshl_add_u64 v[22:23], v[22:23], 0, s[40:41]
	global_load_dword v52, v[22:23], off
	global_load_dword v53, v[22:23], off offset:2048
	v_lshl_add_u64 v[22:23], v[22:23], 0, s[40:41]
	global_load_dword v54, v[22:23], off
	global_load_dword v55, v[22:23], off offset:2048
	v_lshl_add_u64 v[22:23], v[22:23], 0, s[40:41]
	global_load_dword v56, v[22:23], off
	global_load_dword v57, v[22:23], off offset:2048
	v_lshl_add_u64 v[22:23], v[22:23], 0, s[40:41]
	global_load_dword v58, v[22:23], off
	global_load_dword v59, v[22:23], off offset:2048
	v_lshl_add_u64 v[22:23], v[22:23], 0, s[40:41]
	global_load_dword v60, v[22:23], off
	global_load_dword v61, v[22:23], off offset:2048
	v_lshl_add_u64 v[22:23], v[22:23], 0, s[40:41]
	global_load_dword v62, v[22:23], off
	global_load_dword v63, v[22:23], off offset:2048
	v_lshl_add_u64 v[22:23], v[22:23], 0, s[40:41]
	global_load_dword v64, v[22:23], off
	global_load_dword v65, v[22:23], off offset:2048
	v_lshl_add_u64 v[22:23], v[22:23], 0, s[40:41]
	global_load_dword v66, v[22:23], off
	global_load_dword v67, v[22:23], off offset:2048
	v_lshl_add_u64 v[22:23], v[22:23], 0, s[40:41]
	global_load_dword v68, v[22:23], off
	global_load_dword v69, v[22:23], off offset:2048
	v_lshl_add_u64 v[22:23], v[22:23], 0, s[40:41]
	global_load_dword v70, v[22:23], off
	global_load_dword v71, v[22:23], off offset:2048
	v_lshl_add_u64 v[22:23], v[22:23], 0, s[40:41]
	global_load_dword v72, v[22:23], off
	global_load_dword v73, v[22:23], off offset:2048
	v_lshl_add_u64 v[22:23], v[22:23], 0, s[40:41]
	global_load_dword v74, v[22:23], off
	global_load_dword v75, v[22:23], off offset:2048
	v_lshl_add_u64 v[22:23], v[22:23], 0, s[40:41]
	global_load_dword v76, v[22:23], off
	global_load_dword v77, v[22:23], off offset:2048
	v_lshl_add_u64 v[22:23], v[22:23], 0, s[40:41]
	global_load_dword v78, v[22:23], off
	global_load_dword v79, v[22:23], off offset:2048
	v_lshl_add_u64 v[22:23], v[22:23], 0, s[40:41]
	global_load_dword v80, v[22:23], off
	global_load_dword v81, v[22:23], off offset:2048
	v_lshl_add_u64 v[22:23], v[22:23], 0, s[40:41]
	global_load_dword v82, v[22:23], off
	global_load_dword v83, v[22:23], off offset:2048
	v_lshl_add_u64 v[22:23], v[22:23], 0, s[40:41]
	global_load_dword v84, v[22:23], off
	global_load_dword v85, v[22:23], off offset:2048
	v_lshl_add_u64 v[22:23], v[22:23], 0, s[40:41]
	global_load_dword v86, v[22:23], off
	global_load_dword v87, v[22:23], off offset:2048
	v_lshl_add_u64 v[22:23], v[22:23], 0, s[40:41]
	global_load_dword v88, v[22:23], off
	global_load_dword v89, v[22:23], off offset:2048
	v_lshl_add_u64 v[22:23], v[22:23], 0, s[40:41]
	global_load_dword v90, v[22:23], off
	global_load_dword v91, v[22:23], off offset:2048
	v_lshl_add_u64 v[22:23], v[22:23], 0, s[40:41]
	global_load_dword v92, v[22:23], off
	global_load_dword v93, v[22:23], off offset:2048
	v_lshl_add_u32 v25, v5, 8, s2
	s_waitcnt vmcnt(56)
	v_xor_b32_e32 v24, 0, v5
	v_lshl_add_u32 v24, v24, 2, s2
	ds_write_b32 v24, v30
	v_xor_b32_e32 v24, 1, v5
	v_lshl_add_u32 v24, v24, 2, s2
	ds_write_b32 v24, v31 offset:256
	v_xor_b32_e32 v24, 2, v5
	v_lshl_add_u32 v24, v24, 2, s2
	ds_write_b32 v24, v32 offset:512
	v_xor_b32_e32 v24, 3, v5
	v_lshl_add_u32 v24, v24, 2, s2
	ds_write_b32 v24, v33 offset:768
	v_xor_b32_e32 v24, 4, v5
	v_lshl_add_u32 v24, v24, 2, s2
	ds_write_b32 v24, v34 offset:1024
	v_xor_b32_e32 v24, 5, v5
	v_lshl_add_u32 v24, v24, 2, s2
	ds_write_b32 v24, v35 offset:1280
	v_xor_b32_e32 v24, 6, v5
	v_lshl_add_u32 v24, v24, 2, s2
	ds_write_b32 v24, v36 offset:1536
	v_xor_b32_e32 v24, 7, v5
	v_lshl_add_u32 v24, v24, 2, s2
	ds_write_b32 v24, v37 offset:1792
	s_waitcnt vmcnt(48)
	v_xor_b32_e32 v24, 8, v5
	v_lshl_add_u32 v24, v24, 2, s2
	ds_write_b32 v24, v38 offset:2048
	v_xor_b32_e32 v24, 9, v5
	v_lshl_add_u32 v24, v24, 2, s2
	ds_write_b32 v24, v39 offset:2304
	v_xor_b32_e32 v24, 10, v5
	v_lshl_add_u32 v24, v24, 2, s2
	ds_write_b32 v24, v40 offset:2560
	v_xor_b32_e32 v24, 11, v5
	v_lshl_add_u32 v24, v24, 2, s2
	ds_write_b32 v24, v41 offset:2816
	v_xor_b32_e32 v24, 12, v5
	v_lshl_add_u32 v24, v24, 2, s2
	ds_write_b32 v24, v42 offset:3072
	v_xor_b32_e32 v24, 13, v5
	v_lshl_add_u32 v24, v24, 2, s2
	ds_write_b32 v24, v43 offset:3328
	v_xor_b32_e32 v24, 14, v5
	v_lshl_add_u32 v24, v24, 2, s2
	ds_write_b32 v24, v44 offset:3584
	v_xor_b32_e32 v24, 15, v5
	v_lshl_add_u32 v24, v24, 2, s2
	ds_write_b32 v24, v45 offset:3840
	s_waitcnt vmcnt(40)
	v_xor_b32_e32 v24, 16, v5
	v_lshl_add_u32 v24, v24, 2, s2
	ds_write_b32 v24, v46 offset:4096
	v_xor_b32_e32 v24, 17, v5
	v_lshl_add_u32 v24, v24, 2, s2
	ds_write_b32 v24, v47 offset:4352
	v_xor_b32_e32 v24, 18, v5
	v_lshl_add_u32 v24, v24, 2, s2
	ds_write_b32 v24, v48 offset:4608
	v_xor_b32_e32 v24, 19, v5
	v_lshl_add_u32 v24, v24, 2, s2
	ds_write_b32 v24, v49 offset:4864
	v_xor_b32_e32 v24, 20, v5
	v_lshl_add_u32 v24, v24, 2, s2
	ds_write_b32 v24, v50 offset:5120
	v_xor_b32_e32 v24, 21, v5
	v_lshl_add_u32 v24, v24, 2, s2
	ds_write_b32 v24, v51 offset:5376
	v_xor_b32_e32 v24, 22, v5
	v_lshl_add_u32 v24, v24, 2, s2
	ds_write_b32 v24, v52 offset:5632
	v_xor_b32_e32 v24, 23, v5
	v_lshl_add_u32 v24, v24, 2, s2
	ds_write_b32 v24, v53 offset:5888
	s_waitcnt vmcnt(32)
	v_xor_b32_e32 v24, 24, v5
	v_lshl_add_u32 v24, v24, 2, s2
	ds_write_b32 v24, v54 offset:6144
	v_xor_b32_e32 v24, 25, v5
	v_lshl_add_u32 v24, v24, 2, s2
	ds_write_b32 v24, v55 offset:6400
	v_xor_b32_e32 v24, 26, v5
	v_lshl_add_u32 v24, v24, 2, s2
	ds_write_b32 v24, v56 offset:6656
	v_xor_b32_e32 v24, 27, v5
	v_lshl_add_u32 v24, v24, 2, s2
	ds_write_b32 v24, v57 offset:6912
	v_xor_b32_e32 v24, 28, v5
	v_lshl_add_u32 v24, v24, 2, s2
	ds_write_b32 v24, v58 offset:7168
	v_xor_b32_e32 v24, 29, v5
	v_lshl_add_u32 v24, v24, 2, s2
	ds_write_b32 v24, v59 offset:7424
	v_xor_b32_e32 v24, 30, v5
	v_lshl_add_u32 v24, v24, 2, s2
	ds_write_b32 v24, v60 offset:7680
	v_xor_b32_e32 v24, 31, v5
	v_lshl_add_u32 v24, v24, 2, s2
	ds_write_b32 v24, v61 offset:7936
	s_waitcnt vmcnt(24)
	v_xor_b32_e32 v24, 32, v5
	v_lshl_add_u32 v24, v24, 2, s2
	ds_write_b32 v24, v62 offset:8192
	v_xor_b32_e32 v24, 33, v5
	v_lshl_add_u32 v24, v24, 2, s2
	ds_write_b32 v24, v63 offset:8448
	v_xor_b32_e32 v24, 34, v5
	v_lshl_add_u32 v24, v24, 2, s2
	ds_write_b32 v24, v64 offset:8704
	v_xor_b32_e32 v24, 35, v5
	v_lshl_add_u32 v24, v24, 2, s2
	ds_write_b32 v24, v65 offset:8960
	v_xor_b32_e32 v24, 36, v5
	v_lshl_add_u32 v24, v24, 2, s2
	ds_write_b32 v24, v66 offset:9216
	v_xor_b32_e32 v24, 37, v5
	v_lshl_add_u32 v24, v24, 2, s2
	ds_write_b32 v24, v67 offset:9472
	v_xor_b32_e32 v24, 38, v5
	v_lshl_add_u32 v24, v24, 2, s2
	ds_write_b32 v24, v68 offset:9728
	v_xor_b32_e32 v24, 39, v5
	v_lshl_add_u32 v24, v24, 2, s2
	ds_write_b32 v24, v69 offset:9984
	s_waitcnt vmcnt(16)
	v_xor_b32_e32 v24, 40, v5
	v_lshl_add_u32 v24, v24, 2, s2
	ds_write_b32 v24, v70 offset:10240
	v_xor_b32_e32 v24, 41, v5
	v_lshl_add_u32 v24, v24, 2, s2
	ds_write_b32 v24, v71 offset:10496
	v_xor_b32_e32 v24, 42, v5
	v_lshl_add_u32 v24, v24, 2, s2
	ds_write_b32 v24, v72 offset:10752
	v_xor_b32_e32 v24, 43, v5
	v_lshl_add_u32 v24, v24, 2, s2
	ds_write_b32 v24, v73 offset:11008
	v_xor_b32_e32 v24, 44, v5
	v_lshl_add_u32 v24, v24, 2, s2
	ds_write_b32 v24, v74 offset:11264
	v_xor_b32_e32 v24, 45, v5
	v_lshl_add_u32 v24, v24, 2, s2
	ds_write_b32 v24, v75 offset:11520
	v_xor_b32_e32 v24, 46, v5
	v_lshl_add_u32 v24, v24, 2, s2
	ds_write_b32 v24, v76 offset:11776
	v_xor_b32_e32 v24, 47, v5
	v_lshl_add_u32 v24, v24, 2, s2
	ds_write_b32 v24, v77 offset:12032
	s_waitcnt vmcnt(8)
	v_xor_b32_e32 v24, 48, v5
	v_lshl_add_u32 v24, v24, 2, s2
	ds_write_b32 v24, v78 offset:12288
	v_xor_b32_e32 v24, 49, v5
	v_lshl_add_u32 v24, v24, 2, s2
	ds_write_b32 v24, v79 offset:12544
	v_xor_b32_e32 v24, 50, v5
	v_lshl_add_u32 v24, v24, 2, s2
	ds_write_b32 v24, v80 offset:12800
	v_xor_b32_e32 v24, 51, v5
	v_lshl_add_u32 v24, v24, 2, s2
	ds_write_b32 v24, v81 offset:13056
	v_xor_b32_e32 v24, 52, v5
	v_lshl_add_u32 v24, v24, 2, s2
	ds_write_b32 v24, v82 offset:13312
	v_xor_b32_e32 v24, 53, v5
	v_lshl_add_u32 v24, v24, 2, s2
	ds_write_b32 v24, v83 offset:13568
	v_xor_b32_e32 v24, 54, v5
	v_lshl_add_u32 v24, v24, 2, s2
	ds_write_b32 v24, v84 offset:13824
	v_xor_b32_e32 v24, 55, v5
	v_lshl_add_u32 v24, v24, 2, s2
	ds_write_b32 v24, v85 offset:14080
	s_waitcnt vmcnt(0)
	v_xor_b32_e32 v24, 56, v5
	v_lshl_add_u32 v24, v24, 2, s2
	ds_write_b32 v24, v86 offset:14336
	v_xor_b32_e32 v24, 57, v5
	v_lshl_add_u32 v24, v24, 2, s2
	ds_write_b32 v24, v87 offset:14592
	v_xor_b32_e32 v24, 58, v5
	v_lshl_add_u32 v24, v24, 2, s2
	ds_write_b32 v24, v88 offset:14848
	v_xor_b32_e32 v24, 59, v5
	v_lshl_add_u32 v24, v24, 2, s2
	ds_write_b32 v24, v89 offset:15104
	v_xor_b32_e32 v24, 60, v5
	v_lshl_add_u32 v24, v24, 2, s2
	ds_write_b32 v24, v90 offset:15360
	v_xor_b32_e32 v24, 61, v5
	v_lshl_add_u32 v24, v24, 2, s2
	ds_write_b32 v24, v91 offset:15616
	v_xor_b32_e32 v24, 62, v5
	v_lshl_add_u32 v24, v24, 2, s2
	ds_write_b32 v24, v92 offset:15872
	v_xor_b32_e32 v24, 63, v5
	v_lshl_add_u32 v24, v24, 2, s2
	ds_write_b32 v24, v93 offset:16128
	s_waitcnt lgkmcnt(0)
	v_xor_b32_e32 v24, 0, v5
	v_lshl_add_u32 v24, v24, 2, v25
	ds_read_b32 v30, v24
	v_xor_b32_e32 v24, 1, v5
	v_lshl_add_u32 v24, v24, 2, v25
	ds_read_b32 v31, v24
	v_xor_b32_e32 v24, 2, v5
	v_lshl_add_u32 v24, v24, 2, v25
	ds_read_b32 v32, v24
	v_xor_b32_e32 v24, 3, v5
	v_lshl_add_u32 v24, v24, 2, v25
	ds_read_b32 v33, v24
	v_xor_b32_e32 v24, 4, v5
	v_lshl_add_u32 v24, v24, 2, v25
	ds_read_b32 v34, v24
	v_xor_b32_e32 v24, 5, v5
	v_lshl_add_u32 v24, v24, 2, v25
	ds_read_b32 v35, v24
	v_xor_b32_e32 v24, 6, v5
	v_lshl_add_u32 v24, v24, 2, v25
	ds_read_b32 v36, v24
	v_xor_b32_e32 v24, 7, v5
	v_lshl_add_u32 v24, v24, 2, v25
	ds_read_b32 v37, v24
	v_xor_b32_e32 v24, 8, v5
	v_lshl_add_u32 v24, v24, 2, v25
	ds_read_b32 v38, v24
	v_xor_b32_e32 v24, 9, v5
	v_lshl_add_u32 v24, v24, 2, v25
	ds_read_b32 v39, v24
	v_xor_b32_e32 v24, 10, v5
	v_lshl_add_u32 v24, v24, 2, v25
	ds_read_b32 v40, v24
	v_xor_b32_e32 v24, 11, v5
	v_lshl_add_u32 v24, v24, 2, v25
	ds_read_b32 v41, v24
	v_xor_b32_e32 v24, 12, v5
	v_lshl_add_u32 v24, v24, 2, v25
	ds_read_b32 v42, v24
	v_xor_b32_e32 v24, 13, v5
	v_lshl_add_u32 v24, v24, 2, v25
	ds_read_b32 v43, v24
	v_xor_b32_e32 v24, 14, v5
	v_lshl_add_u32 v24, v24, 2, v25
	ds_read_b32 v44, v24
	v_xor_b32_e32 v24, 15, v5
	v_lshl_add_u32 v24, v24, 2, v25
	ds_read_b32 v45, v24
	v_xor_b32_e32 v24, 16, v5
	v_lshl_add_u32 v24, v24, 2, v25
	ds_read_b32 v46, v24
	v_xor_b32_e32 v24, 17, v5
	v_lshl_add_u32 v24, v24, 2, v25
	ds_read_b32 v47, v24
	v_xor_b32_e32 v24, 18, v5
	v_lshl_add_u32 v24, v24, 2, v25
	ds_read_b32 v48, v24
	v_xor_b32_e32 v24, 19, v5
	v_lshl_add_u32 v24, v24, 2, v25
	ds_read_b32 v49, v24
	v_xor_b32_e32 v24, 20, v5
	v_lshl_add_u32 v24, v24, 2, v25
	ds_read_b32 v50, v24
	v_xor_b32_e32 v24, 21, v5
	v_lshl_add_u32 v24, v24, 2, v25
	ds_read_b32 v51, v24
	v_xor_b32_e32 v24, 22, v5
	v_lshl_add_u32 v24, v24, 2, v25
	ds_read_b32 v52, v24
	v_xor_b32_e32 v24, 23, v5
	v_lshl_add_u32 v24, v24, 2, v25
	ds_read_b32 v53, v24
	v_xor_b32_e32 v24, 24, v5
	v_lshl_add_u32 v24, v24, 2, v25
	ds_read_b32 v54, v24
	v_xor_b32_e32 v24, 25, v5
	v_lshl_add_u32 v24, v24, 2, v25
	ds_read_b32 v55, v24
	v_xor_b32_e32 v24, 26, v5
	v_lshl_add_u32 v24, v24, 2, v25
	ds_read_b32 v56, v24
	v_xor_b32_e32 v24, 27, v5
	v_lshl_add_u32 v24, v24, 2, v25
	ds_read_b32 v57, v24
	v_xor_b32_e32 v24, 28, v5
	v_lshl_add_u32 v24, v24, 2, v25
	ds_read_b32 v58, v24
	v_xor_b32_e32 v24, 29, v5
	v_lshl_add_u32 v24, v24, 2, v25
	ds_read_b32 v59, v24
	v_xor_b32_e32 v24, 30, v5
	v_lshl_add_u32 v24, v24, 2, v25
	ds_read_b32 v60, v24
	v_xor_b32_e32 v24, 31, v5
	v_lshl_add_u32 v24, v24, 2, v25
	ds_read_b32 v61, v24
	v_xor_b32_e32 v24, 32, v5
	v_lshl_add_u32 v24, v24, 2, v25
	ds_read_b32 v62, v24
	v_xor_b32_e32 v24, 33, v5
	v_lshl_add_u32 v24, v24, 2, v25
	ds_read_b32 v63, v24
	v_xor_b32_e32 v24, 34, v5
	v_lshl_add_u32 v24, v24, 2, v25
	ds_read_b32 v64, v24
	v_xor_b32_e32 v24, 35, v5
	v_lshl_add_u32 v24, v24, 2, v25
	ds_read_b32 v65, v24
	v_xor_b32_e32 v24, 36, v5
	v_lshl_add_u32 v24, v24, 2, v25
	ds_read_b32 v66, v24
	v_xor_b32_e32 v24, 37, v5
	v_lshl_add_u32 v24, v24, 2, v25
	ds_read_b32 v67, v24
	v_xor_b32_e32 v24, 38, v5
	v_lshl_add_u32 v24, v24, 2, v25
	ds_read_b32 v68, v24
	v_xor_b32_e32 v24, 39, v5
	v_lshl_add_u32 v24, v24, 2, v25
	ds_read_b32 v69, v24
	v_xor_b32_e32 v24, 40, v5
	v_lshl_add_u32 v24, v24, 2, v25
	ds_read_b32 v70, v24
	v_xor_b32_e32 v24, 41, v5
	v_lshl_add_u32 v24, v24, 2, v25
	ds_read_b32 v71, v24
	v_xor_b32_e32 v24, 42, v5
	v_lshl_add_u32 v24, v24, 2, v25
	ds_read_b32 v72, v24
	v_xor_b32_e32 v24, 43, v5
	v_lshl_add_u32 v24, v24, 2, v25
	ds_read_b32 v73, v24
	v_xor_b32_e32 v24, 44, v5
	v_lshl_add_u32 v24, v24, 2, v25
	ds_read_b32 v74, v24
	v_xor_b32_e32 v24, 45, v5
	v_lshl_add_u32 v24, v24, 2, v25
	ds_read_b32 v75, v24
	v_xor_b32_e32 v24, 46, v5
	v_lshl_add_u32 v24, v24, 2, v25
	ds_read_b32 v76, v24
	v_xor_b32_e32 v24, 47, v5
	v_lshl_add_u32 v24, v24, 2, v25
	ds_read_b32 v77, v24
	v_xor_b32_e32 v24, 48, v5
	v_lshl_add_u32 v24, v24, 2, v25
	ds_read_b32 v78, v24
	v_xor_b32_e32 v24, 49, v5
	v_lshl_add_u32 v24, v24, 2, v25
	ds_read_b32 v79, v24
	v_xor_b32_e32 v24, 50, v5
	v_lshl_add_u32 v24, v24, 2, v25
	ds_read_b32 v80, v24
	v_xor_b32_e32 v24, 51, v5
	v_lshl_add_u32 v24, v24, 2, v25
	ds_read_b32 v81, v24
	v_xor_b32_e32 v24, 52, v5
	v_lshl_add_u32 v24, v24, 2, v25
	ds_read_b32 v82, v24
	v_xor_b32_e32 v24, 53, v5
	v_lshl_add_u32 v24, v24, 2, v25
	ds_read_b32 v83, v24
	v_xor_b32_e32 v24, 54, v5
	v_lshl_add_u32 v24, v24, 2, v25
	ds_read_b32 v84, v24
	v_xor_b32_e32 v24, 55, v5
	v_lshl_add_u32 v24, v24, 2, v25
	ds_read_b32 v85, v24
	v_xor_b32_e32 v24, 56, v5
	v_lshl_add_u32 v24, v24, 2, v25
	ds_read_b32 v86, v24
	v_xor_b32_e32 v24, 57, v5
	v_lshl_add_u32 v24, v24, 2, v25
	ds_read_b32 v87, v24
	v_xor_b32_e32 v24, 58, v5
	v_lshl_add_u32 v24, v24, 2, v25
	ds_read_b32 v88, v24
	v_xor_b32_e32 v24, 59, v5
	v_lshl_add_u32 v24, v24, 2, v25
	ds_read_b32 v89, v24
	v_xor_b32_e32 v24, 60, v5
	v_lshl_add_u32 v24, v24, 2, v25
	ds_read_b32 v90, v24
	v_xor_b32_e32 v24, 61, v5
	v_lshl_add_u32 v24, v24, 2, v25
	ds_read_b32 v91, v24
	v_xor_b32_e32 v24, 62, v5
	v_lshl_add_u32 v24, v24, 2, v25
	ds_read_b32 v92, v24
	v_xor_b32_e32 v24, 63, v5
	v_lshl_add_u32 v24, v24, 2, v25
	ds_read_b32 v93, v24
	s_waitcnt lgkmcnt(0)
	v_add_f32_e32 v18, v18, v30
	v_add_f32_e32 v18, v18, v31
	v_add_f32_e32 v18, v18, v32
	v_add_f32_e32 v18, v18, v33
	v_add_f32_e32 v18, v18, v34
	v_add_f32_e32 v18, v18, v35
	v_add_f32_e32 v18, v18, v36
	v_add_f32_e32 v18, v18, v37
	v_add_f32_e32 v18, v18, v38
	v_add_f32_e32 v18, v18, v39
	v_add_f32_e32 v18, v18, v40
	v_add_f32_e32 v18, v18, v41
	v_add_f32_e32 v18, v18, v42
	v_add_f32_e32 v18, v18, v43
	v_add_f32_e32 v18, v18, v44
	v_add_f32_e32 v18, v18, v45
	v_add_f32_e32 v18, v18, v46
	v_add_f32_e32 v18, v18, v47
	v_add_f32_e32 v18, v18, v48
	v_add_f32_e32 v18, v18, v49
	v_add_f32_e32 v18, v18, v50
	v_add_f32_e32 v18, v18, v51
	v_add_f32_e32 v18, v18, v52
	v_add_f32_e32 v18, v18, v53
	v_add_f32_e32 v18, v18, v54
	v_add_f32_e32 v18, v18, v55
	v_add_f32_e32 v18, v18, v56
	v_add_f32_e32 v18, v18, v57
	v_add_f32_e32 v18, v18, v58
	v_add_f32_e32 v18, v18, v59
	v_add_f32_e32 v18, v18, v60
	v_add_f32_e32 v18, v18, v61
	v_add_f32_e32 v18, v18, v62
	v_add_f32_e32 v18, v18, v63
	v_add_f32_e32 v18, v18, v64
	v_add_f32_e32 v18, v18, v65
	v_add_f32_e32 v18, v18, v66
	v_add_f32_e32 v18, v18, v67
	v_add_f32_e32 v18, v18, v68
	v_add_f32_e32 v18, v18, v69
	v_add_f32_e32 v18, v18, v70
	v_add_f32_e32 v18, v18, v71
	v_add_f32_e32 v18, v18, v72
	v_add_f32_e32 v18, v18, v73
	v_add_f32_e32 v18, v18, v74
	v_add_f32_e32 v18, v18, v75
	v_add_f32_e32 v18, v18, v76
	v_add_f32_e32 v18, v18, v77
	v_add_f32_e32 v18, v18, v78
	v_add_f32_e32 v18, v18, v79
	v_add_f32_e32 v18, v18, v80
	v_add_f32_e32 v18, v18, v81
	v_add_f32_e32 v18, v18, v82
	v_add_f32_e32 v18, v18, v83
	v_add_f32_e32 v18, v18, v84
	v_add_f32_e32 v18, v18, v85
	v_add_f32_e32 v18, v18, v86
	v_add_f32_e32 v18, v18, v87
	v_add_f32_e32 v18, v18, v88
	v_add_f32_e32 v18, v18, v89
	v_add_f32_e32 v18, v18, v90
	v_add_f32_e32 v18, v18, v91
	v_add_f32_e32 v18, v18, v92
	v_add_f32_e32 v18, v18, v93
	ds_bpermute_b32 v2, v1, v18
	s_waitcnt lgkmcnt(0)
	v_add_f32_e32 v2, v18, v2
	v_cndmask_b32_e64 v2, v2, v18, s[0:1]
	ds_bpermute_b32 v8, v12, v2
	s_waitcnt lgkmcnt(0)
	v_add_f32_e32 v8, v2, v8
	v_cndmask_b32_e64 v2, v8, v2, s[14:15]
	ds_bpermute_b32 v8, v13, v2
	s_waitcnt lgkmcnt(0)
	v_add_f32_e32 v8, v2, v8
	v_cndmask_b32_e64 v2, v8, v2, s[4:5]
	ds_bpermute_b32 v8, v14, v2
	s_waitcnt lgkmcnt(0)
	v_add_f32_e32 v8, v2, v8
	v_cndmask_b32_e64 v2, v8, v2, s[6:7]
	ds_bpermute_b32 v8, v15, v2
	s_waitcnt lgkmcnt(0)
	v_add_f32_e32 v8, v2, v8
	v_cndmask_b32_e64 v10, v8, v2, s[8:9]
	ds_bpermute_b32 v11, v16, v10
	v_lshlrev_b32_e32 v2, 2, v4
	v_lshl_add_u64 v[8:9], s[36:37], 0, v[2:3]
	s_waitcnt lgkmcnt(0)
	v_add_f32_e32 v2, v10, v11
	v_cndmask_b32_e64 v2, v2, v10, s[10:11]
	v_sub_f32_e32 v18, v2, v18
	v_add_f32_e32 v18, v18, v30
	v_mul_f32_e32 v30, 0x3fb8aa3b, v18
	v_add_f32_e32 v18, v18, v31
	v_mul_f32_e32 v31, 0x3fb8aa3b, v18
	v_add_f32_e32 v18, v18, v32
	v_mul_f32_e32 v32, 0x3fb8aa3b, v18
	v_add_f32_e32 v18, v18, v33
	v_mul_f32_e32 v33, 0x3fb8aa3b, v18
	v_add_f32_e32 v18, v18, v34
	v_mul_f32_e32 v34, 0x3fb8aa3b, v18
	v_add_f32_e32 v18, v18, v35
	v_mul_f32_e32 v35, 0x3fb8aa3b, v18
	v_add_f32_e32 v18, v18, v36
	v_mul_f32_e32 v36, 0x3fb8aa3b, v18
	v_add_f32_e32 v18, v18, v37
	v_mul_f32_e32 v37, 0x3fb8aa3b, v18
	v_add_f32_e32 v18, v18, v38
	v_mul_f32_e32 v38, 0x3fb8aa3b, v18
	v_add_f32_e32 v18, v18, v39
	v_mul_f32_e32 v39, 0x3fb8aa3b, v18
	v_add_f32_e32 v18, v18, v40
	v_mul_f32_e32 v40, 0x3fb8aa3b, v18
	v_add_f32_e32 v18, v18, v41
	v_mul_f32_e32 v41, 0x3fb8aa3b, v18
	v_add_f32_e32 v18, v18, v42
	v_mul_f32_e32 v42, 0x3fb8aa3b, v18
	v_add_f32_e32 v18, v18, v43
	v_mul_f32_e32 v43, 0x3fb8aa3b, v18
	v_add_f32_e32 v18, v18, v44
	v_mul_f32_e32 v44, 0x3fb8aa3b, v18
	v_add_f32_e32 v18, v18, v45
	v_mul_f32_e32 v45, 0x3fb8aa3b, v18
	v_add_f32_e32 v18, v18, v46
	v_mul_f32_e32 v46, 0x3fb8aa3b, v18
	v_add_f32_e32 v18, v18, v47
	v_mul_f32_e32 v47, 0x3fb8aa3b, v18
	v_add_f32_e32 v18, v18, v48
	v_mul_f32_e32 v48, 0x3fb8aa3b, v18
	v_add_f32_e32 v18, v18, v49
	v_mul_f32_e32 v49, 0x3fb8aa3b, v18
	v_add_f32_e32 v18, v18, v50
	v_mul_f32_e32 v50, 0x3fb8aa3b, v18
	v_add_f32_e32 v18, v18, v51
	v_mul_f32_e32 v51, 0x3fb8aa3b, v18
	v_add_f32_e32 v18, v18, v52
	v_mul_f32_e32 v52, 0x3fb8aa3b, v18
	v_add_f32_e32 v18, v18, v53
	v_mul_f32_e32 v53, 0x3fb8aa3b, v18
	v_add_f32_e32 v18, v18, v54
	v_mul_f32_e32 v54, 0x3fb8aa3b, v18
	v_add_f32_e32 v18, v18, v55
	v_mul_f32_e32 v55, 0x3fb8aa3b, v18
	v_add_f32_e32 v18, v18, v56
	v_mul_f32_e32 v56, 0x3fb8aa3b, v18
	v_add_f32_e32 v18, v18, v57
	v_mul_f32_e32 v57, 0x3fb8aa3b, v18
	v_add_f32_e32 v18, v18, v58
	v_mul_f32_e32 v58, 0x3fb8aa3b, v18
	v_add_f32_e32 v18, v18, v59
	v_mul_f32_e32 v59, 0x3fb8aa3b, v18
	v_add_f32_e32 v18, v18, v60
	v_mul_f32_e32 v60, 0x3fb8aa3b, v18
	v_add_f32_e32 v18, v18, v61
	v_mul_f32_e32 v61, 0x3fb8aa3b, v18
	v_add_f32_e32 v18, v18, v62
	v_mul_f32_e32 v62, 0x3fb8aa3b, v18
	v_add_f32_e32 v18, v18, v63
	v_mul_f32_e32 v63, 0x3fb8aa3b, v18
	v_add_f32_e32 v18, v18, v64
	v_mul_f32_e32 v64, 0x3fb8aa3b, v18
	v_add_f32_e32 v18, v18, v65
	v_mul_f32_e32 v65, 0x3fb8aa3b, v18
	v_add_f32_e32 v18, v18, v66
	v_mul_f32_e32 v66, 0x3fb8aa3b, v18
	v_add_f32_e32 v18, v18, v67
	v_mul_f32_e32 v67, 0x3fb8aa3b, v18
	v_add_f32_e32 v18, v18, v68
	v_mul_f32_e32 v68, 0x3fb8aa3b, v18
	v_add_f32_e32 v18, v18, v69
	v_mul_f32_e32 v69, 0x3fb8aa3b, v18
	v_add_f32_e32 v18, v18, v70
	v_mul_f32_e32 v70, 0x3fb8aa3b, v18
	v_add_f32_e32 v18, v18, v71
	v_mul_f32_e32 v71, 0x3fb8aa3b, v18
	v_add_f32_e32 v18, v18, v72
	v_mul_f32_e32 v72, 0x3fb8aa3b, v18
	v_add_f32_e32 v18, v18, v73
	v_mul_f32_e32 v73, 0x3fb8aa3b, v18
	v_add_f32_e32 v18, v18, v74
	v_mul_f32_e32 v74, 0x3fb8aa3b, v18
	v_add_f32_e32 v18, v18, v75
	v_mul_f32_e32 v75, 0x3fb8aa3b, v18
	v_add_f32_e32 v18, v18, v76
	v_mul_f32_e32 v76, 0x3fb8aa3b, v18
	v_add_f32_e32 v18, v18, v77
	v_mul_f32_e32 v77, 0x3fb8aa3b, v18
	v_add_f32_e32 v18, v18, v78
	v_mul_f32_e32 v78, 0x3fb8aa3b, v18
	v_add_f32_e32 v18, v18, v79
	v_mul_f32_e32 v79, 0x3fb8aa3b, v18
	v_add_f32_e32 v18, v18, v80
	v_mul_f32_e32 v80, 0x3fb8aa3b, v18
	v_add_f32_e32 v18, v18, v81
	v_mul_f32_e32 v81, 0x3fb8aa3b, v18
	v_add_f32_e32 v18, v18, v82
	v_mul_f32_e32 v82, 0x3fb8aa3b, v18
	v_add_f32_e32 v18, v18, v83
	v_mul_f32_e32 v83, 0x3fb8aa3b, v18
	v_add_f32_e32 v18, v18, v84
	v_mul_f32_e32 v84, 0x3fb8aa3b, v18
	v_add_f32_e32 v18, v18, v85
	v_mul_f32_e32 v85, 0x3fb8aa3b, v18
	v_add_f32_e32 v18, v18, v86
	v_mul_f32_e32 v86, 0x3fb8aa3b, v18
	v_add_f32_e32 v18, v18, v87
	v_mul_f32_e32 v87, 0x3fb8aa3b, v18
	v_add_f32_e32 v18, v18, v88
	v_mul_f32_e32 v88, 0x3fb8aa3b, v18
	v_add_f32_e32 v18, v18, v89
	v_mul_f32_e32 v89, 0x3fb8aa3b, v18
	v_add_f32_e32 v18, v18, v90
	v_mul_f32_e32 v90, 0x3fb8aa3b, v18
	v_add_f32_e32 v18, v18, v91
	v_mul_f32_e32 v91, 0x3fb8aa3b, v18
	v_add_f32_e32 v18, v18, v92
	v_mul_f32_e32 v92, 0x3fb8aa3b, v18
	v_add_f32_e32 v18, v18, v93
	v_mul_f32_e32 v93, 0x3fb8aa3b, v18
	v_xor_b32_e32 v24, 0, v5
	v_lshl_add_u32 v24, v24, 2, v25
	ds_write_b32 v24, v30
	v_xor_b32_e32 v24, 1, v5
	v_lshl_add_u32 v24, v24, 2, v25
	ds_write_b32 v24, v31
	v_xor_b32_e32 v24, 2, v5
	v_lshl_add_u32 v24, v24, 2, v25
	ds_write_b32 v24, v32
	v_xor_b32_e32 v24, 3, v5
	v_lshl_add_u32 v24, v24, 2, v25
	ds_write_b32 v24, v33
	v_xor_b32_e32 v24, 4, v5
	v_lshl_add_u32 v24, v24, 2, v25
	ds_write_b32 v24, v34
	v_xor_b32_e32 v24, 5, v5
	v_lshl_add_u32 v24, v24, 2, v25
	ds_write_b32 v24, v35
	v_xor_b32_e32 v24, 6, v5
	v_lshl_add_u32 v24, v24, 2, v25
	ds_write_b32 v24, v36
	v_xor_b32_e32 v24, 7, v5
	v_lshl_add_u32 v24, v24, 2, v25
	ds_write_b32 v24, v37
	v_xor_b32_e32 v24, 8, v5
	v_lshl_add_u32 v24, v24, 2, v25
	ds_write_b32 v24, v38
	v_xor_b32_e32 v24, 9, v5
	v_lshl_add_u32 v24, v24, 2, v25
	ds_write_b32 v24, v39
	v_xor_b32_e32 v24, 10, v5
	v_lshl_add_u32 v24, v24, 2, v25
	ds_write_b32 v24, v40
	v_xor_b32_e32 v24, 11, v5
	v_lshl_add_u32 v24, v24, 2, v25
	ds_write_b32 v24, v41
	v_xor_b32_e32 v24, 12, v5
	v_lshl_add_u32 v24, v24, 2, v25
	ds_write_b32 v24, v42
	v_xor_b32_e32 v24, 13, v5
	v_lshl_add_u32 v24, v24, 2, v25
	ds_write_b32 v24, v43
	v_xor_b32_e32 v24, 14, v5
	v_lshl_add_u32 v24, v24, 2, v25
	ds_write_b32 v24, v44
	v_xor_b32_e32 v24, 15, v5
	v_lshl_add_u32 v24, v24, 2, v25
	ds_write_b32 v24, v45
	v_xor_b32_e32 v24, 16, v5
	v_lshl_add_u32 v24, v24, 2, v25
	ds_write_b32 v24, v46
	v_xor_b32_e32 v24, 17, v5
	v_lshl_add_u32 v24, v24, 2, v25
	ds_write_b32 v24, v47
	v_xor_b32_e32 v24, 18, v5
	v_lshl_add_u32 v24, v24, 2, v25
	ds_write_b32 v24, v48
	v_xor_b32_e32 v24, 19, v5
	v_lshl_add_u32 v24, v24, 2, v25
	ds_write_b32 v24, v49
	v_xor_b32_e32 v24, 20, v5
	v_lshl_add_u32 v24, v24, 2, v25
	ds_write_b32 v24, v50
	v_xor_b32_e32 v24, 21, v5
	v_lshl_add_u32 v24, v24, 2, v25
	ds_write_b32 v24, v51
	v_xor_b32_e32 v24, 22, v5
	v_lshl_add_u32 v24, v24, 2, v25
	ds_write_b32 v24, v52
	v_xor_b32_e32 v24, 23, v5
	v_lshl_add_u32 v24, v24, 2, v25
	ds_write_b32 v24, v53
	v_xor_b32_e32 v24, 24, v5
	v_lshl_add_u32 v24, v24, 2, v25
	ds_write_b32 v24, v54
	v_xor_b32_e32 v24, 25, v5
	v_lshl_add_u32 v24, v24, 2, v25
	ds_write_b32 v24, v55
	v_xor_b32_e32 v24, 26, v5
	v_lshl_add_u32 v24, v24, 2, v25
	ds_write_b32 v24, v56
	v_xor_b32_e32 v24, 27, v5
	v_lshl_add_u32 v24, v24, 2, v25
	ds_write_b32 v24, v57
	v_xor_b32_e32 v24, 28, v5
	v_lshl_add_u32 v24, v24, 2, v25
	ds_write_b32 v24, v58
	v_xor_b32_e32 v24, 29, v5
	v_lshl_add_u32 v24, v24, 2, v25
	ds_write_b32 v24, v59
	v_xor_b32_e32 v24, 30, v5
	v_lshl_add_u32 v24, v24, 2, v25
	ds_write_b32 v24, v60
	v_xor_b32_e32 v24, 31, v5
	v_lshl_add_u32 v24, v24, 2, v25
	ds_write_b32 v24, v61
	v_xor_b32_e32 v24, 32, v5
	v_lshl_add_u32 v24, v24, 2, v25
	ds_write_b32 v24, v62
	v_xor_b32_e32 v24, 33, v5
	v_lshl_add_u32 v24, v24, 2, v25
	ds_write_b32 v24, v63
	v_xor_b32_e32 v24, 34, v5
	v_lshl_add_u32 v24, v24, 2, v25
	ds_write_b32 v24, v64
	v_xor_b32_e32 v24, 35, v5
	v_lshl_add_u32 v24, v24, 2, v25
	ds_write_b32 v24, v65
	v_xor_b32_e32 v24, 36, v5
	v_lshl_add_u32 v24, v24, 2, v25
	ds_write_b32 v24, v66
	v_xor_b32_e32 v24, 37, v5
	v_lshl_add_u32 v24, v24, 2, v25
	ds_write_b32 v24, v67
	v_xor_b32_e32 v24, 38, v5
	v_lshl_add_u32 v24, v24, 2, v25
	ds_write_b32 v24, v68
	v_xor_b32_e32 v24, 39, v5
	v_lshl_add_u32 v24, v24, 2, v25
	ds_write_b32 v24, v69
	v_xor_b32_e32 v24, 40, v5
	v_lshl_add_u32 v24, v24, 2, v25
	ds_write_b32 v24, v70
	v_xor_b32_e32 v24, 41, v5
	v_lshl_add_u32 v24, v24, 2, v25
	ds_write_b32 v24, v71
	v_xor_b32_e32 v24, 42, v5
	v_lshl_add_u32 v24, v24, 2, v25
	ds_write_b32 v24, v72
	v_xor_b32_e32 v24, 43, v5
	v_lshl_add_u32 v24, v24, 2, v25
	ds_write_b32 v24, v73
	v_xor_b32_e32 v24, 44, v5
	v_lshl_add_u32 v24, v24, 2, v25
	ds_write_b32 v24, v74
	v_xor_b32_e32 v24, 45, v5
	v_lshl_add_u32 v24, v24, 2, v25
	ds_write_b32 v24, v75
	v_xor_b32_e32 v24, 46, v5
	v_lshl_add_u32 v24, v24, 2, v25
	ds_write_b32 v24, v76
	v_xor_b32_e32 v24, 47, v5
	v_lshl_add_u32 v24, v24, 2, v25
	ds_write_b32 v24, v77
	v_xor_b32_e32 v24, 48, v5
	v_lshl_add_u32 v24, v24, 2, v25
	ds_write_b32 v24, v78
	v_xor_b32_e32 v24, 49, v5
	v_lshl_add_u32 v24, v24, 2, v25
	ds_write_b32 v24, v79
	v_xor_b32_e32 v24, 50, v5
	v_lshl_add_u32 v24, v24, 2, v25
	ds_write_b32 v24, v80
	v_xor_b32_e32 v24, 51, v5
	v_lshl_add_u32 v24, v24, 2, v25
	ds_write_b32 v24, v81
	v_xor_b32_e32 v24, 52, v5
	v_lshl_add_u32 v24, v24, 2, v25
	ds_write_b32 v24, v82
	v_xor_b32_e32 v24, 53, v5
	v_lshl_add_u32 v24, v24, 2, v25
	ds_write_b32 v24, v83
	v_xor_b32_e32 v24, 54, v5
	v_lshl_add_u32 v24, v24, 2, v25
	ds_write_b32 v24, v84
	v_xor_b32_e32 v24, 55, v5
	v_lshl_add_u32 v24, v24, 2, v25
	ds_write_b32 v24, v85
	v_xor_b32_e32 v24, 56, v5
	v_lshl_add_u32 v24, v24, 2, v25
	ds_write_b32 v24, v86
	v_xor_b32_e32 v24, 57, v5
	v_lshl_add_u32 v24, v24, 2, v25
	ds_write_b32 v24, v87
	v_xor_b32_e32 v24, 58, v5
	v_lshl_add_u32 v24, v24, 2, v25
	ds_write_b32 v24, v88
	v_xor_b32_e32 v24, 59, v5
	v_lshl_add_u32 v24, v24, 2, v25
	ds_write_b32 v24, v89
	v_xor_b32_e32 v24, 60, v5
	v_lshl_add_u32 v24, v24, 2, v25
	ds_write_b32 v24, v90
	v_xor_b32_e32 v24, 61, v5
	v_lshl_add_u32 v24, v24, 2, v25
	ds_write_b32 v24, v91
	v_xor_b32_e32 v24, 62, v5
	v_lshl_add_u32 v24, v24, 2, v25
	ds_write_b32 v24, v92
	v_xor_b32_e32 v24, 63, v5
	v_lshl_add_u32 v24, v24, 2, v25
	ds_write_b32 v24, v93
	v_lshlrev_b32_e32 v22, 2, v5
	v_mov_b32_e32 v23, 0
	v_lshl_add_u64 v[22:23], v[22:23], 0, s[36:37]
	s_waitcnt lgkmcnt(0)
	v_xor_b32_e32 v24, 0, v5
	v_lshl_add_u32 v24, v24, 2, s2
	ds_read_b32 v30, v24
	v_xor_b32_e32 v24, 1, v5
	v_lshl_add_u32 v24, v24, 2, s2
	ds_read_b32 v31, v24 offset:256
	v_xor_b32_e32 v24, 2, v5
	v_lshl_add_u32 v24, v24, 2, s2
	ds_read_b32 v32, v24 offset:512
	v_xor_b32_e32 v24, 3, v5
	v_lshl_add_u32 v24, v24, 2, s2
	ds_read_b32 v33, v24 offset:768
	v_xor_b32_e32 v24, 4, v5
	v_lshl_add_u32 v24, v24, 2, s2
	ds_read_b32 v34, v24 offset:1024
	v_xor_b32_e32 v24, 5, v5
	v_lshl_add_u32 v24, v24, 2, s2
	ds_read_b32 v35, v24 offset:1280
	v_xor_b32_e32 v24, 6, v5
	v_lshl_add_u32 v24, v24, 2, s2
	ds_read_b32 v36, v24 offset:1536
	v_xor_b32_e32 v24, 7, v5
	v_lshl_add_u32 v24, v24, 2, s2
	ds_read_b32 v37, v24 offset:1792
	v_xor_b32_e32 v24, 8, v5
	v_lshl_add_u32 v24, v24, 2, s2
	ds_read_b32 v38, v24 offset:2048
	v_xor_b32_e32 v24, 9, v5
	v_lshl_add_u32 v24, v24, 2, s2
	ds_read_b32 v39, v24 offset:2304
	v_xor_b32_e32 v24, 10, v5
	v_lshl_add_u32 v24, v24, 2, s2
	ds_read_b32 v40, v24 offset:2560
	v_xor_b32_e32 v24, 11, v5
	v_lshl_add_u32 v24, v24, 2, s2
	ds_read_b32 v41, v24 offset:2816
	v_xor_b32_e32 v24, 12, v5
	v_lshl_add_u32 v24, v24, 2, s2
	ds_read_b32 v42, v24 offset:3072
	v_xor_b32_e32 v24, 13, v5
	v_lshl_add_u32 v24, v24, 2, s2
	ds_read_b32 v43, v24 offset:3328
	v_xor_b32_e32 v24, 14, v5
	v_lshl_add_u32 v24, v24, 2, s2
	ds_read_b32 v44, v24 offset:3584
	v_xor_b32_e32 v24, 15, v5
	v_lshl_add_u32 v24, v24, 2, s2
	ds_read_b32 v45, v24 offset:3840
	v_xor_b32_e32 v24, 16, v5
	v_lshl_add_u32 v24, v24, 2, s2
	ds_read_b32 v46, v24 offset:4096
	v_xor_b32_e32 v24, 17, v5
	v_lshl_add_u32 v24, v24, 2, s2
	ds_read_b32 v47, v24 offset:4352
	v_xor_b32_e32 v24, 18, v5
	v_lshl_add_u32 v24, v24, 2, s2
	ds_read_b32 v48, v24 offset:4608
	v_xor_b32_e32 v24, 19, v5
	v_lshl_add_u32 v24, v24, 2, s2
	ds_read_b32 v49, v24 offset:4864
	v_xor_b32_e32 v24, 20, v5
	v_lshl_add_u32 v24, v24, 2, s2
	ds_read_b32 v50, v24 offset:5120
	v_xor_b32_e32 v24, 21, v5
	v_lshl_add_u32 v24, v24, 2, s2
	ds_read_b32 v51, v24 offset:5376
	v_xor_b32_e32 v24, 22, v5
	v_lshl_add_u32 v24, v24, 2, s2
	ds_read_b32 v52, v24 offset:5632
	v_xor_b32_e32 v24, 23, v5
	v_lshl_add_u32 v24, v24, 2, s2
	ds_read_b32 v53, v24 offset:5888
	v_xor_b32_e32 v24, 24, v5
	v_lshl_add_u32 v24, v24, 2, s2
	ds_read_b32 v54, v24 offset:6144
	v_xor_b32_e32 v24, 25, v5
	v_lshl_add_u32 v24, v24, 2, s2
	ds_read_b32 v55, v24 offset:6400
	v_xor_b32_e32 v24, 26, v5
	v_lshl_add_u32 v24, v24, 2, s2
	ds_read_b32 v56, v24 offset:6656
	v_xor_b32_e32 v24, 27, v5
	v_lshl_add_u32 v24, v24, 2, s2
	ds_read_b32 v57, v24 offset:6912
	v_xor_b32_e32 v24, 28, v5
	v_lshl_add_u32 v24, v24, 2, s2
	ds_read_b32 v58, v24 offset:7168
	v_xor_b32_e32 v24, 29, v5
	v_lshl_add_u32 v24, v24, 2, s2
	ds_read_b32 v59, v24 offset:7424
	v_xor_b32_e32 v24, 30, v5
	v_lshl_add_u32 v24, v24, 2, s2
	ds_read_b32 v60, v24 offset:7680
	v_xor_b32_e32 v24, 31, v5
	v_lshl_add_u32 v24, v24, 2, s2
	ds_read_b32 v61, v24 offset:7936
	v_xor_b32_e32 v24, 32, v5
	v_lshl_add_u32 v24, v24, 2, s2
	ds_read_b32 v62, v24 offset:8192
	v_xor_b32_e32 v24, 33, v5
	v_lshl_add_u32 v24, v24, 2, s2
	ds_read_b32 v63, v24 offset:8448
	v_xor_b32_e32 v24, 34, v5
	v_lshl_add_u32 v24, v24, 2, s2
	ds_read_b32 v64, v24 offset:8704
	v_xor_b32_e32 v24, 35, v5
	v_lshl_add_u32 v24, v24, 2, s2
	ds_read_b32 v65, v24 offset:8960
	v_xor_b32_e32 v24, 36, v5
	v_lshl_add_u32 v24, v24, 2, s2
	ds_read_b32 v66, v24 offset:9216
	v_xor_b32_e32 v24, 37, v5
	v_lshl_add_u32 v24, v24, 2, s2
	ds_read_b32 v67, v24 offset:9472
	v_xor_b32_e32 v24, 38, v5
	v_lshl_add_u32 v24, v24, 2, s2
	ds_read_b32 v68, v24 offset:9728
	v_xor_b32_e32 v24, 39, v5
	v_lshl_add_u32 v24, v24, 2, s2
	ds_read_b32 v69, v24 offset:9984
	v_xor_b32_e32 v24, 40, v5
	v_lshl_add_u32 v24, v24, 2, s2
	ds_read_b32 v70, v24 offset:10240
	v_xor_b32_e32 v24, 41, v5
	v_lshl_add_u32 v24, v24, 2, s2
	ds_read_b32 v71, v24 offset:10496
	v_xor_b32_e32 v24, 42, v5
	v_lshl_add_u32 v24, v24, 2, s2
	ds_read_b32 v72, v24 offset:10752
	v_xor_b32_e32 v24, 43, v5
	v_lshl_add_u32 v24, v24, 2, s2
	ds_read_b32 v73, v24 offset:11008
	v_xor_b32_e32 v24, 44, v5
	v_lshl_add_u32 v24, v24, 2, s2
	ds_read_b32 v74, v24 offset:11264
	v_xor_b32_e32 v24, 45, v5
	v_lshl_add_u32 v24, v24, 2, s2
	ds_read_b32 v75, v24 offset:11520
	v_xor_b32_e32 v24, 46, v5
	v_lshl_add_u32 v24, v24, 2, s2
	ds_read_b32 v76, v24 offset:11776
	v_xor_b32_e32 v24, 47, v5
	v_lshl_add_u32 v24, v24, 2, s2
	ds_read_b32 v77, v24 offset:12032
	v_xor_b32_e32 v24, 48, v5
	v_lshl_add_u32 v24, v24, 2, s2
	ds_read_b32 v78, v24 offset:12288
	v_xor_b32_e32 v24, 49, v5
	v_lshl_add_u32 v24, v24, 2, s2
	ds_read_b32 v79, v24 offset:12544
	v_xor_b32_e32 v24, 50, v5
	v_lshl_add_u32 v24, v24, 2, s2
	ds_read_b32 v80, v24 offset:12800
	v_xor_b32_e32 v24, 51, v5
	v_lshl_add_u32 v24, v24, 2, s2
	ds_read_b32 v81, v24 offset:13056
	v_xor_b32_e32 v24, 52, v5
	v_lshl_add_u32 v24, v24, 2, s2
	ds_read_b32 v82, v24 offset:13312
	v_xor_b32_e32 v24, 53, v5
	v_lshl_add_u32 v24, v24, 2, s2
	ds_read_b32 v83, v24 offset:13568
	v_xor_b32_e32 v24, 54, v5
	v_lshl_add_u32 v24, v24, 2, s2
	ds_read_b32 v84, v24 offset:13824
	v_xor_b32_e32 v24, 55, v5
	v_lshl_add_u32 v24, v24, 2, s2
	ds_read_b32 v85, v24 offset:14080
	v_xor_b32_e32 v24, 56, v5
	v_lshl_add_u32 v24, v24, 2, s2
	ds_read_b32 v86, v24 offset:14336
	v_xor_b32_e32 v24, 57, v5
	v_lshl_add_u32 v24, v24, 2, s2
	ds_read_b32 v87, v24 offset:14592
	v_xor_b32_e32 v24, 58, v5
	v_lshl_add_u32 v24, v24, 2, s2
	ds_read_b32 v88, v24 offset:14848
	v_xor_b32_e32 v24, 59, v5
	v_lshl_add_u32 v24, v24, 2, s2
	ds_read_b32 v89, v24 offset:15104
	v_xor_b32_e32 v24, 60, v5
	v_lshl_add_u32 v24, v24, 2, s2
	ds_read_b32 v90, v24 offset:15360
	v_xor_b32_e32 v24, 61, v5
	v_lshl_add_u32 v24, v24, 2, s2
	ds_read_b32 v91, v24 offset:15616
	v_xor_b32_e32 v24, 62, v5
	v_lshl_add_u32 v24, v24, 2, s2
	ds_read_b32 v92, v24 offset:15872
	v_xor_b32_e32 v24, 63, v5
	v_lshl_add_u32 v24, v24, 2, s2
	ds_read_b32 v93, v24 offset:16128
	s_waitcnt lgkmcnt(0)
	global_store_dword v[22:23], v30, off
	global_store_dword v[22:23], v31, off offset:256
	global_store_dword v[22:23], v32, off offset:512
	global_store_dword v[22:23], v33, off offset:768
	global_store_dword v[22:23], v34, off offset:1024
	global_store_dword v[22:23], v35, off offset:1280
	global_store_dword v[22:23], v36, off offset:1536
	global_store_dword v[22:23], v37, off offset:1792
	global_store_dword v[22:23], v38, off offset:2048
	global_store_dword v[22:23], v39, off offset:2304
	global_store_dword v[22:23], v40, off offset:2560
	global_store_dword v[22:23], v41, off offset:2816
	global_store_dword v[22:23], v42, off offset:3072
	global_store_dword v[22:23], v43, off offset:3328
	global_store_dword v[22:23], v44, off offset:3584
	global_store_dword v[22:23], v45, off offset:3840
	v_lshl_add_u64 v[22:23], v[22:23], 0, s[40:41]
	global_store_dword v[22:23], v46, off
	global_store_dword v[22:23], v47, off offset:256
	global_store_dword v[22:23], v48, off offset:512
	global_store_dword v[22:23], v49, off offset:768
	global_store_dword v[22:23], v50, off offset:1024
	global_store_dword v[22:23], v51, off offset:1280
	global_store_dword v[22:23], v52, off offset:1536
	global_store_dword v[22:23], v53, off offset:1792
	global_store_dword v[22:23], v54, off offset:2048
	global_store_dword v[22:23], v55, off offset:2304
	global_store_dword v[22:23], v56, off offset:2560
	global_store_dword v[22:23], v57, off offset:2816
	global_store_dword v[22:23], v58, off offset:3072
	global_store_dword v[22:23], v59, off offset:3328
	global_store_dword v[22:23], v60, off offset:3584
	global_store_dword v[22:23], v61, off offset:3840
	v_lshl_add_u64 v[22:23], v[22:23], 0, s[40:41]
	global_store_dword v[22:23], v62, off
	global_store_dword v[22:23], v63, off offset:256
	global_store_dword v[22:23], v64, off offset:512
	global_store_dword v[22:23], v65, off offset:768
	global_store_dword v[22:23], v66, off offset:1024
	global_store_dword v[22:23], v67, off offset:1280
	global_store_dword v[22:23], v68, off offset:1536
	global_store_dword v[22:23], v69, off offset:1792
	global_store_dword v[22:23], v70, off offset:2048
	global_store_dword v[22:23], v71, off offset:2304
	global_store_dword v[22:23], v72, off offset:2560
	global_store_dword v[22:23], v73, off offset:2816
	global_store_dword v[22:23], v74, off offset:3072
	global_store_dword v[22:23], v75, off offset:3328
	global_store_dword v[22:23], v76, off offset:3584
	global_store_dword v[22:23], v77, off offset:3840
	v_lshl_add_u64 v[22:23], v[22:23], 0, s[40:41]
	global_store_dword v[22:23], v78, off
	global_store_dword v[22:23], v79, off offset:256
	global_store_dword v[22:23], v80, off offset:512
	global_store_dword v[22:23], v81, off offset:768
	global_store_dword v[22:23], v82, off offset:1024
	global_store_dword v[22:23], v83, off offset:1280
	global_store_dword v[22:23], v84, off offset:1536
	global_store_dword v[22:23], v85, off offset:1792
	global_store_dword v[22:23], v86, off offset:2048
	global_store_dword v[22:23], v87, off offset:2304
	global_store_dword v[22:23], v88, off offset:2560
	global_store_dword v[22:23], v89, off offset:2816
	global_store_dword v[22:23], v90, off offset:3072
	global_store_dword v[22:23], v91, off offset:3328
	global_store_dword v[22:23], v92, off offset:3584
	global_store_dword v[22:23], v93, off offset:3840
	s_barrier
	s_branch .LBB0_357
.Lcs_sample:
	v_readfirstlane_b32 s2, v227
	v_lshlrev_b32_e32 v22, 5, v5
	v_mov_b32_e32 v23, 0
	s_lshl_b32 s40, s21, 2
	s_add_u32 s40, s22, s40
	s_addc_u32 s41, s23, 0
	s_add_u32 s40, s40, 0x9280000
	s_addc_u32 s41, s41, 0
	s_lshr_b32 s2, s2, 6
	s_lshl_b32 s2, s2, 13
	v_lshl_add_u64 v[26:27], v[22:23], 0, s[40:41]
	v_lshl_add_u64 v[22:23], v[22:23], 0, s[34:35]
	s_mov_b32 s40, 0x1000
	s_mov_b32 s41, 0
	v_mov_b32_e32 v62, 0
	global_load_dword v30, v[22:23], off
	global_load_dword v31, v[22:23], off offset:2048
	v_lshl_add_u64 v[22:23], v[22:23], 0, s[40:41]
	global_load_dword v32, v[22:23], off
	global_load_dword v33, v[22:23], off offset:2048
	v_lshl_add_u64 v[22:23], v[22:23], 0, s[40:41]
	global_load_dword v34, v[22:23], off
	global_load_dword v35, v[22:23], off offset:2048
	v_lshl_add_u64 v[22:23], v[22:23], 0, s[40:41]
	global_load_dword v36, v[22:23], off
	global_load_dword v37, v[22:23], off offset:2048
	v_lshl_add_u64 v[22:23], v[22:23], 0, s[40:41]
	global_load_dword v38, v[22:23], off
	global_load_dword v39, v[22:23], off offset:2048
	v_lshl_add_u64 v[22:23], v[22:23], 0, s[40:41]
	global_load_dword v40, v[22:23], off
	global_load_dword v41, v[22:23], off offset:2048
	v_lshl_add_u64 v[22:23], v[22:23], 0, s[40:41]
	global_load_dword v42, v[22:23], off
	global_load_dword v43, v[22:23], off offset:2048
	v_lshl_add_u64 v[22:23], v[22:23], 0, s[40:41]
	global_load_dword v44, v[22:23], off
	global_load_dword v45, v[22:23], off offset:2048
	v_lshl_add_u64 v[22:23], v[22:23], 0, s[40:41]
	global_load_dword v46, v[22:23], off
	global_load_dword v47, v[22:23], off offset:2048
	v_lshl_add_u64 v[22:23], v[22:23], 0, s[40:41]
	global_load_dword v48, v[22:23], off
	global_load_dword v49, v[22:23], off offset:2048
	v_lshl_add_u64 v[22:23], v[22:23], 0, s[40:41]
	global_load_dword v50, v[22:23], off
	global_load_dword v51, v[22:23], off offset:2048
	v_lshl_add_u64 v[22:23], v[22:23], 0, s[40:41]
	global_load_dword v52, v[22:23], off
	global_load_dword v53, v[22:23], off offset:2048
	v_lshl_add_u64 v[22:23], v[22:23], 0, s[40:41]
	global_load_dword v54, v[22:23], off
	global_load_dword v55, v[22:23], off offset:2048
	v_lshl_add_u64 v[22:23], v[22:23], 0, s[40:41]
	global_load_dword v56, v[22:23], off
	global_load_dword v57, v[22:23], off offset:2048
	v_lshl_add_u64 v[22:23], v[22:23], 0, s[40:41]
	global_load_dword v58, v[22:23], off
	global_load_dword v59, v[22:23], off offset:2048
	v_lshl_add_u64 v[22:23], v[22:23], 0, s[40:41]
	global_load_dword v60, v[22:23], off
	global_load_dword v61, v[22:23], off offset:2048
	s_mov_b64 exec, 0xffff
	global_load_dword v62, v[26:27], off
	s_mov_b64 exec, -1
	v_lshrrev_b32_e32 v26, 1, v5
	v_and_b32_e32 v27, 1, v5
	v_lshlrev_b32_e32 v27, 5, v27
	v_lshl_add_u32 v25, v26, 8, s2
	s_waitcnt vmcnt(25)
	v_xor_b32_e32 v24, 0, v5
	v_lshl_add_u32 v24, v24, 2, s2
	ds_write_b32 v24, v30
	v_xor_b32_e32 v24, 1, v5
	v_lshl_add_u32 v24, v24, 2, s2
	ds_write_b32 v24, v31 offset:256
	v_xor_b32_e32 v24, 2, v5
	v_lshl_add_u32 v24, v24, 2, s2
	ds_write_b32 v24, v32 offset:512
	v_xor_b32_e32 v24, 3, v5
	v_lshl_add_u32 v24, v24, 2, s2
	ds_write_b32 v24, v33 offset:768
	v_xor_b32_e32 v24, 4, v5
	v_lshl_add_u32 v24, v24, 2, s2
	ds_write_b32 v24, v34 offset:1024
	v_xor_b32_e32 v24, 5, v5
	v_lshl_add_u32 v24, v24, 2, s2
	ds_write_b32 v24, v35 offset:1280
	v_xor_b32_e32 v24, 6, v5
	v_lshl_add_u32 v24, v24, 2, s2
	ds_write_b32 v24, v36 offset:1536
	v_xor_b32_e32 v24, 7, v5
	v_lshl_add_u32 v24, v24, 2, s2
	ds_write_b32 v24, v37 offset:1792
	s_waitcnt vmcnt(17)
	v_xor_b32_e32 v24, 8, v5
	v_lshl_add_u32 v24, v24, 2, s2
	ds_write_b32 v24, v38 offset:2048
	v_xor_b32_e32 v24, 9, v5
	v_lshl_add_u32 v24, v24, 2, s2
	ds_write_b32 v24, v39 offset:2304
	v_xor_b32_e32 v24, 10, v5
	v_lshl_add_u32 v24, v24, 2, s2
	ds_write_b32 v24, v40 offset:2560
	v_xor_b32_e32 v24, 11, v5
	v_lshl_add_u32 v24, v24, 2, s2
	ds_write_b32 v24, v41 offset:2816
	v_xor_b32_e32 v24, 12, v5
	v_lshl_add_u32 v24, v24, 2, s2
	ds_write_b32 v24, v42 offset:3072
	v_xor_b32_e32 v24, 13, v5
	v_lshl_add_u32 v24, v24, 2, s2
	ds_write_b32 v24, v43 offset:3328
	v_xor_b32_e32 v24, 14, v5
	v_lshl_add_u32 v24, v24, 2, s2
	ds_write_b32 v24, v44 offset:3584
	v_xor_b32_e32 v24, 15, v5
	v_lshl_add_u32 v24, v24, 2, s2
	ds_write_b32 v24, v45 offset:3840
	s_waitcnt vmcnt(9)
	v_xor_b32_e32 v24, 16, v5
	v_lshl_add_u32 v24, v24, 2, s2
	ds_write_b32 v24, v46 offset:4096
	v_xor_b32_e32 v24, 17, v5
	v_lshl_add_u32 v24, v24, 2, s2
	ds_write_b32 v24, v47 offset:4352
	v_xor_b32_e32 v24, 18, v5
	v_lshl_add_u32 v24, v24, 2, s2
	ds_write_b32 v24, v48 offset:4608
	v_xor_b32_e32 v24, 19, v5
	v_lshl_add_u32 v24, v24, 2, s2
	ds_write_b32 v24, v49 offset:4864
	v_xor_b32_e32 v24, 20, v5
	v_lshl_add_u32 v24, v24, 2, s2
	ds_write_b32 v24, v50 offset:5120
	v_xor_b32_e32 v24, 21, v5
	v_lshl_add_u32 v24, v24, 2, s2
	ds_write_b32 v24, v51 offset:5376
	v_xor_b32_e32 v24, 22, v5
	v_lshl_add_u32 v24, v24, 2, s2
	ds_write_b32 v24, v52 offset:5632
	v_xor_b32_e32 v24, 23, v5
	v_lshl_add_u32 v24, v24, 2, s2
	ds_write_b32 v24, v53 offset:5888
	s_waitcnt vmcnt(1)
	v_xor_b32_e32 v24, 24, v5
	v_lshl_add_u32 v24, v24, 2, s2
	ds_write_b32 v24, v54 offset:6144
	v_xor_b32_e32 v24, 25, v5
	v_lshl_add_u32 v24, v24, 2, s2
	ds_write_b32 v24, v55 offset:6400
	v_xor_b32_e32 v24, 26, v5
	v_lshl_add_u32 v24, v24, 2, s2
	ds_write_b32 v24, v56 offset:6656
	v_xor_b32_e32 v24, 27, v5
	v_lshl_add_u32 v24, v24, 2, s2
	ds_write_b32 v24, v57 offset:6912
	v_xor_b32_e32 v24, 28, v5
	v_lshl_add_u32 v24, v24, 2, s2
	ds_write_b32 v24, v58 offset:7168
	v_xor_b32_e32 v24, 29, v5
	v_lshl_add_u32 v24, v24, 2, s2
	ds_write_b32 v24, v59 offset:7424
	v_xor_b32_e32 v24, 30, v5
	v_lshl_add_u32 v24, v24, 2, s2
	ds_write_b32 v24, v60 offset:7680
	v_xor_b32_e32 v24, 31, v5
	v_lshl_add_u32 v24, v24, 2, s2
	ds_write_b32 v24, v61 offset:7936
	s_waitcnt lgkmcnt(0)
	v_add_u32_e32 v24, 0, v27
	v_xor_b32_e32 v24, v24, v26
	v_lshl_add_u32 v24, v24, 2, v25
	ds_read_b32 v30, v24
	v_add_u32_e32 v24, 1, v27
	v_xor_b32_e32 v24, v24, v26
	v_lshl_add_u32 v24, v24, 2, v25
	ds_read_b32 v31, v24
	v_add_u32_e32 v24, 2, v27
	v_xor_b32_e32 v24, v24, v26
	v_lshl_add_u32 v24, v24, 2, v25
	ds_read_b32 v32, v24
	v_add_u32_e32 v24, 3, v27
	v_xor_b32_e32 v24, v24, v26
	v_lshl_add_u32 v24, v24, 2, v25
	ds_read_b32 v33, v24
	v_add_u32_e32 v24, 4, v27
	v_xor_b32_e32 v24, v24, v26
	v_lshl_add_u32 v24, v24, 2, v25
	ds_read_b32 v34, v24
	v_add_u32_e32 v24, 5, v27
	v_xor_b32_e32 v24, v24, v26
	v_lshl_add_u32 v24, v24, 2, v25
	ds_read_b32 v35, v24
	v_add_u32_e32 v24, 6, v27
	v_xor_b32_e32 v24, v24, v26
	v_lshl_add_u32 v24, v24, 2, v25
	ds_read_b32 v36, v24
	v_add_u32_e32 v24, 7, v27
	v_xor_b32_e32 v24, v24, v26
	v_lshl_add_u32 v24, v24, 2, v25
	ds_read_b32 v37, v24
	v_add_u32_e32 v24, 8, v27
	v_xor_b32_e32 v24, v24, v26
	v_lshl_add_u32 v24, v24, 2, v25
	ds_read_b32 v38, v24
	v_add_u32_e32 v24, 9, v27
	v_xor_b32_e32 v24, v24, v26
	v_lshl_add_u32 v24, v24, 2, v25
	ds_read_b32 v39, v24
	v_add_u32_e32 v24, 10, v27
	v_xor_b32_e32 v24, v24, v26
	v_lshl_add_u32 v24, v24, 2, v25
	ds_read_b32 v40, v24
	v_add_u32_e32 v24, 11, v27
	v_xor_b32_e32 v24, v24, v26
	v_lshl_add_u32 v24, v24, 2, v25
	ds_read_b32 v41, v24
	v_add_u32_e32 v24, 12, v27
	v_xor_b32_e32 v24, v24, v26
	v_lshl_add_u32 v24, v24, 2, v25
	ds_read_b32 v42, v24
	v_add_u32_e32 v24, 13, v27
	v_xor_b32_e32 v24, v24, v26
	v_lshl_add_u32 v24, v24, 2, v25
	ds_read_b32 v43, v24
	v_add_u32_e32 v24, 14, v27
	v_xor_b32_e32 v24, v24, v26
	v_lshl_add_u32 v24, v24, 2, v25
	ds_read_b32 v44, v24
	v_add_u32_e32 v24, 15, v27
	v_xor_b32_e32 v24, v24, v26
	v_lshl_add_u32 v24, v24, 2, v25
	ds_read_b32 v45, v24
	v_add_u32_e32 v24, 16, v27
	v_xor_b32_e32 v24, v24, v26
	v_lshl_add_u32 v24, v24, 2, v25
	ds_read_b32 v46, v24
	v_add_u32_e32 v24, 17, v27
	v_xor_b32_e32 v24, v24, v26
	v_lshl_add_u32 v24, v24, 2, v25
	ds_read_b32 v47, v24
	v_add_u32_e32 v24, 18, v27
	v_xor_b32_e32 v24, v24, v26
	v_lshl_add_u32 v24, v24, 2, v25
	ds_read_b32 v48, v24
	v_add_u32_e32 v24, 19, v27
	v_xor_b32_e32 v24, v24, v26
	v_lshl_add_u32 v24, v24, 2, v25
	ds_read_b32 v49, v24
	v_add_u32_e32 v24, 20, v27
	v_xor_b32_e32 v24, v24, v26
	v_lshl_add_u32 v24, v24, 2, v25
	ds_read_b32 v50, v24
	v_add_u32_e32 v24, 21, v27
	v_xor_b32_e32 v24, v24, v26
	v_lshl_add_u32 v24, v24, 2, v25
	ds_read_b32 v51, v24
	v_add_u32_e32 v24, 22, v27
	v_xor_b32_e32 v24, v24, v26
	v_lshl_add_u32 v24, v24, 2, v25
	ds_read_b32 v52, v24
	v_add_u32_e32 v24, 23, v27
	v_xor_b32_e32 v24, v24, v26
	v_lshl_add_u32 v24, v24, 2, v25
	ds_read_b32 v53, v24
	v_add_u32_e32 v24, 24, v27
	v_xor_b32_e32 v24, v24, v26
	v_lshl_add_u32 v24, v24, 2, v25
	ds_read_b32 v54, v24
	v_add_u32_e32 v24, 25, v27
	v_xor_b32_e32 v24, v24, v26
	v_lshl_add_u32 v24, v24, 2, v25
	ds_read_b32 v55, v24
	v_add_u32_e32 v24, 26, v27
	v_xor_b32_e32 v24, v24, v26
	v_lshl_add_u32 v24, v24, 2, v25
	ds_read_b32 v56, v24
	v_add_u32_e32 v24, 27, v27
	v_xor_b32_e32 v24, v24, v26
	v_lshl_add_u32 v24, v24, 2, v25
	ds_read_b32 v57, v24
	v_add_u32_e32 v24, 28, v27
	v_xor_b32_e32 v24, v24, v26
	v_lshl_add_u32 v24, v24, 2, v25
	ds_read_b32 v58, v24
	v_add_u32_e32 v24, 29, v27
	v_xor_b32_e32 v24, v24, v26
	v_lshl_add_u32 v24, v24, 2, v25
	ds_read_b32 v59, v24
	v_add_u32_e32 v24, 30, v27
	v_xor_b32_e32 v24, v24, v26
	v_lshl_add_u32 v24, v24, 2, v25
	ds_read_b32 v60, v24
	v_add_u32_e32 v24, 31, v27
	v_xor_b32_e32 v24, v24, v26
	v_lshl_add_u32 v24, v24, 2, v25
	ds_read_b32 v61, v24
	s_waitcnt lgkmcnt(0)
	v_add_f32_e32 v18, v18, v30
	v_add_f32_e32 v18, v18, v31
	v_add_f32_e32 v18, v18, v32
	v_add_f32_e32 v18, v18, v33
	v_add_f32_e32 v18, v18, v34
	v_add_f32_e32 v18, v18, v35
	v_add_f32_e32 v18, v18, v36
	v_add_f32_e32 v18, v18, v37
	v_add_f32_e32 v18, v18, v38
	v_add_f32_e32 v18, v18, v39
	v_add_f32_e32 v18, v18, v40
	v_add_f32_e32 v18, v18, v41
	v_add_f32_e32 v18, v18, v42
	v_add_f32_e32 v18, v18, v43
	v_add_f32_e32 v18, v18, v44
	v_add_f32_e32 v18, v18, v45
	v_add_f32_e32 v18, v18, v46
	v_add_f32_e32 v18, v18, v47
	v_add_f32_e32 v18, v18, v48
	v_add_f32_e32 v18, v18, v49
	v_add_f32_e32 v18, v18, v50
	v_add_f32_e32 v18, v18, v51
	v_add_f32_e32 v18, v18, v52
	v_add_f32_e32 v18, v18, v53
	v_add_f32_e32 v18, v18, v54
	v_add_f32_e32 v18, v18, v55
	v_add_f32_e32 v18, v18, v56
	v_add_f32_e32 v18, v18, v57
	v_add_f32_e32 v18, v18, v58
	v_add_f32_e32 v18, v18, v59
	v_add_f32_e32 v18, v18, v60
	v_add_f32_e32 v18, v18, v61
	ds_bpermute_b32 v2, v1, v18
	s_waitcnt lgkmcnt(0)
	v_add_f32_e32 v2, v18, v2
	v_cndmask_b32_e64 v2, v2, v18, s[0:1]
	ds_bpermute_b32 v8, v12, v2
	s_waitcnt lgkmcnt(0)
	v_add_f32_e32 v8, v2, v8
	v_cndmask_b32_e64 v2, v8, v2, s[14:15]
	ds_bpermute_b32 v8, v13, v2
	s_waitcnt lgkmcnt(0)
	v_add_f32_e32 v8, v2, v8
	v_cndmask_b32_e64 v2, v8, v2, s[4:5]
	ds_bpermute_b32 v8, v14, v2
	s_waitcnt lgkmcnt(0)
	v_add_f32_e32 v8, v2, v8
	v_cndmask_b32_e64 v2, v8, v2, s[6:7]
	ds_bpermute_b32 v8, v15, v2
	s_waitcnt lgkmcnt(0)
	v_add_f32_e32 v8, v2, v8
	v_cndmask_b32_e64 v10, v8, v2, s[8:9]
	ds_bpermute_b32 v11, v16, v10
	v_lshlrev_b32_e32 v2, 2, v4
	v_lshl_add_u64 v[8:9], s[36:37], 0, v[2:3]
	s_waitcnt lgkmcnt(0)
	v_add_f32_e32 v2, v10, v11
	v_cndmask_b32_e64 v2, v2, v10, s[10:11]
	v_sub_f32_e32 v18, v2, v18
	s_nop 0
	v_readlane_b32 s41, v2, 63
	v_add_f32_e32 v18, v18, v30
	v_mul_f32_e32 v30, 0x3fb8aa3b, v18
	v_add_f32_e32 v18, v18, v31
	v_mul_f32_e32 v31, 0x3fb8aa3b, v18
	v_add_f32_e32 v18, v18, v32
	v_mul_f32_e32 v32, 0x3fb8aa3b, v18
	v_add_f32_e32 v18, v18, v33
	v_mul_f32_e32 v33, 0x3fb8aa3b, v18
	v_add_f32_e32 v18, v18, v34
	v_mul_f32_e32 v34, 0x3fb8aa3b, v18
	v_add_f32_e32 v18, v18, v35
	v_mul_f32_e32 v35, 0x3fb8aa3b, v18
	v_add_f32_e32 v18, v18, v36
	v_mul_f32_e32 v36, 0x3fb8aa3b, v18
	v_add_f32_e32 v18, v18, v37
	v_mul_f32_e32 v37, 0x3fb8aa3b, v18
	v_add_f32_e32 v18, v18, v38
	v_mul_f32_e32 v38, 0x3fb8aa3b, v18
	v_add_f32_e32 v18, v18, v39
	v_mul_f32_e32 v39, 0x3fb8aa3b, v18
	v_add_f32_e32 v18, v18, v40
	v_mul_f32_e32 v40, 0x3fb8aa3b, v18
	v_add_f32_e32 v18, v18, v41
	v_mul_f32_e32 v41, 0x3fb8aa3b, v18
	v_add_f32_e32 v18, v18, v42
	v_mul_f32_e32 v42, 0x3fb8aa3b, v18
	v_add_f32_e32 v18, v18, v43
	v_mul_f32_e32 v43, 0x3fb8aa3b, v18
	v_add_f32_e32 v18, v18, v44
	v_mul_f32_e32 v44, 0x3fb8aa3b, v18
	v_add_f32_e32 v18, v18, v45
	v_mul_f32_e32 v45, 0x3fb8aa3b, v18
	v_add_f32_e32 v18, v18, v46
	v_mul_f32_e32 v46, 0x3fb8aa3b, v18
	v_add_f32_e32 v18, v18, v47
	v_mul_f32_e32 v47, 0x3fb8aa3b, v18
	v_add_f32_e32 v18, v18, v48
	v_mul_f32_e32 v48, 0x3fb8aa3b, v18
	v_add_f32_e32 v18, v18, v49
	v_mul_f32_e32 v49, 0x3fb8aa3b, v18
	v_add_f32_e32 v18, v18, v50
	v_mul_f32_e32 v50, 0x3fb8aa3b, v18
	v_add_f32_e32 v18, v18, v51
	v_mul_f32_e32 v51, 0x3fb8aa3b, v18
	v_add_f32_e32 v18, v18, v52
	v_mul_f32_e32 v52, 0x3fb8aa3b, v18
	v_add_f32_e32 v18, v18, v53
	v_mul_f32_e32 v53, 0x3fb8aa3b, v18
	v_add_f32_e32 v18, v18, v54
	v_mul_f32_e32 v54, 0x3fb8aa3b, v18
	v_add_f32_e32 v18, v18, v55
	v_mul_f32_e32 v55, 0x3fb8aa3b, v18
	v_add_f32_e32 v18, v18, v56
	v_mul_f32_e32 v56, 0x3fb8aa3b, v18
	v_add_f32_e32 v18, v18, v57
	v_mul_f32_e32 v57, 0x3fb8aa3b, v18
	v_add_f32_e32 v18, v18, v58
	v_mul_f32_e32 v58, 0x3fb8aa3b, v18
	v_add_f32_e32 v18, v18, v59
	v_mul_f32_e32 v59, 0x3fb8aa3b, v18
	v_add_f32_e32 v18, v18, v60
	v_mul_f32_e32 v60, 0x3fb8aa3b, v18
	v_add_f32_e32 v18, v18, v61
	v_mul_f32_e32 v61, 0x3fb8aa3b, v18
	v_add_u32_e32 v24, 0, v27
	v_xor_b32_e32 v24, v24, v26
	v_lshl_add_u32 v24, v24, 2, v25
	ds_write_b32 v24, v30
	v_add_u32_e32 v24, 1, v27
	v_xor_b32_e32 v24, v24, v26
	v_lshl_add_u32 v24, v24, 2, v25
	ds_write_b32 v24, v31
	v_add_u32_e32 v24, 2, v27
	v_xor_b32_e32 v24, v24, v26
	v_lshl_add_u32 v24, v24, 2, v25
	ds_write_b32 v24, v32
	v_add_u32_e32 v24, 3, v27
	v_xor_b32_e32 v24, v24, v26
	v_lshl_add_u32 v24, v24, 2, v25
	ds_write_b32 v24, v33
	v_add_u32_e32 v24, 4, v27
	v_xor_b32_e32 v24, v24, v26
	v_lshl_add_u32 v24, v24, 2, v25
	ds_write_b32 v24, v34
	v_add_u32_e32 v24, 5, v27
	v_xor_b32_e32 v24, v24, v26
	v_lshl_add_u32 v24, v24, 2, v25
	ds_write_b32 v24, v35
	v_add_u32_e32 v24, 6, v27
	v_xor_b32_e32 v24, v24, v26
	v_lshl_add_u32 v24, v24, 2, v25
	ds_write_b32 v24, v36
	v_add_u32_e32 v24, 7, v27
	v_xor_b32_e32 v24, v24, v26
	v_lshl_add_u32 v24, v24, 2, v25
	ds_write_b32 v24, v37
	v_add_u32_e32 v24, 8, v27
	v_xor_b32_e32 v24, v24, v26
	v_lshl_add_u32 v24, v24, 2, v25
	ds_write_b32 v24, v38
	v_add_u32_e32 v24, 9, v27
	v_xor_b32_e32 v24, v24, v26
	v_lshl_add_u32 v24, v24, 2, v25
	ds_write_b32 v24, v39
	v_add_u32_e32 v24, 10, v27
	v_xor_b32_e32 v24, v24, v26
	v_lshl_add_u32 v24, v24, 2, v25
	ds_write_b32 v24, v40
	v_add_u32_e32 v24, 11, v27
	v_xor_b32_e32 v24, v24, v26
	v_lshl_add_u32 v24, v24, 2, v25
	ds_write_b32 v24, v41
	v_add_u32_e32 v24, 12, v27
	v_xor_b32_e32 v24, v24, v26
	v_lshl_add_u32 v24, v24, 2, v25
	ds_write_b32 v24, v42
	v_add_u32_e32 v24, 13, v27
	v_xor_b32_e32 v24, v24, v26
	v_lshl_add_u32 v24, v24, 2, v25
	ds_write_b32 v24, v43
	v_add_u32_e32 v24, 14, v27
	v_xor_b32_e32 v24, v24, v26
	v_lshl_add_u32 v24, v24, 2, v25
	ds_write_b32 v24, v44
	v_add_u32_e32 v24, 15, v27
	v_xor_b32_e32 v24, v24, v26
	v_lshl_add_u32 v24, v24, 2, v25
	ds_write_b32 v24, v45
	v_add_u32_e32 v24, 16, v27
	v_xor_b32_e32 v24, v24, v26
	v_lshl_add_u32 v24, v24, 2, v25
	ds_write_b32 v24, v46
	v_add_u32_e32 v24, 17, v27
	v_xor_b32_e32 v24, v24, v26
	v_lshl_add_u32 v24, v24, 2, v25
	ds_write_b32 v24, v47
	v_add_u32_e32 v24, 18, v27
	v_xor_b32_e32 v24, v24, v26
	v_lshl_add_u32 v24, v24, 2, v25
	ds_write_b32 v24, v48
	v_add_u32_e32 v24, 19, v27
	v_xor_b32_e32 v24, v24, v26
	v_lshl_add_u32 v24, v24, 2, v25
	ds_write_b32 v24, v49
	v_add_u32_e32 v24, 20, v27
	v_xor_b32_e32 v24, v24, v26
	v_lshl_add_u32 v24, v24, 2, v25
	ds_write_b32 v24, v50
	v_add_u32_e32 v24, 21, v27
	v_xor_b32_e32 v24, v24, v26
	v_lshl_add_u32 v24, v24, 2, v25
	ds_write_b32 v24, v51
	v_add_u32_e32 v24, 22, v27
	v_xor_b32_e32 v24, v24, v26
	v_lshl_add_u32 v24, v24, 2, v25
	ds_write_b32 v24, v52
	v_add_u32_e32 v24, 23, v27
	v_xor_b32_e32 v24, v24, v26
	v_lshl_add_u32 v24, v24, 2, v25
	ds_write_b32 v24, v53
	v_add_u32_e32 v24, 24, v27
	v_xor_b32_e32 v24, v24, v26
	v_lshl_add_u32 v24, v24, 2, v25
	ds_write_b32 v24, v54
	v_add_u32_e32 v24, 25, v27
	v_xor_b32_e32 v24, v24, v26
	v_lshl_add_u32 v24, v24, 2, v25
	ds_write_b32 v24, v55
	v_add_u32_e32 v24, 26, v27
	v_xor_b32_e32 v24, v24, v26
	v_lshl_add_u32 v24, v24, 2, v25
	ds_write_b32 v24, v56
	v_add_u32_e32 v24, 27, v27
	v_xor_b32_e32 v24, v24, v26
	v_lshl_add_u32 v24, v24, 2, v25
	ds_write_b32 v24, v57
	v_add_u32_e32 v24, 28, v27
	v_xor_b32_e32 v24, v24, v26
	v_lshl_add_u32 v24, v24, 2, v25
	ds_write_b32 v24, v58
	v_add_u32_e32 v24, 29, v27
	v_xor_b32_e32 v24, v24, v26
	v_lshl_add_u32 v24, v24, 2, v25
	ds_write_b32 v24, v59
	v_add_u32_e32 v24, 30, v27
	v_xor_b32_e32 v24, v24, v26
	v_lshl_add_u32 v24, v24, 2, v25
	ds_write_b32 v24, v60
	v_add_u32_e32 v24, 31, v27
	v_xor_b32_e32 v24, v24, v26
	v_lshl_add_u32 v24, v24, 2, v25
	ds_write_b32 v24, v61
	s_waitcnt vmcnt(0)
	ds_bpermute_b32 v8, v1, v62
	s_waitcnt lgkmcnt(0)
	v_add_f32_e32 v8, v62, v8
	v_cndmask_b32_e64 v63, v8, v62, s[0:1]
	ds_bpermute_b32 v8, v12, v63
	s_waitcnt lgkmcnt(0)
	v_add_f32_e32 v8, v63, v8
	v_cndmask_b32_e64 v63, v8, v63, s[14:15]
	ds_bpermute_b32 v8, v13, v63
	s_waitcnt lgkmcnt(0)
	v_add_f32_e32 v8, v63, v8
	v_cndmask_b32_e64 v63, v8, v63, s[4:5]
	ds_bpermute_b32 v8, v14, v63
	s_waitcnt lgkmcnt(0)
	v_add_f32_e32 v8, v63, v8
	v_cndmask_b32_e64 v63, v8, v63, s[6:7]
	v_add_f32_e32 v63, s41, v63
	v_mul_f32_e32 v63, 0x3fb8aa3b, v63
	v_lshlrev_b32_e32 v22, 2, v5
	v_mov_b32_e32 v23, 0
	v_lshl_add_u64 v[22:23], v[22:23], 0, s[36:37]
	s_mov_b32 s40, 0x1000
	s_mov_b32 s41, 0
	s_waitcnt lgkmcnt(0)
	v_xor_b32_e32 v24, 0, v5
	v_lshl_add_u32 v24, v24, 2, s2
	ds_read_b32 v30, v24
	v_xor_b32_e32 v24, 1, v5
	v_lshl_add_u32 v24, v24, 2, s2
	ds_read_b32 v31, v24 offset:256
	v_xor_b32_e32 v24, 2, v5
	v_lshl_add_u32 v24, v24, 2, s2
	ds_read_b32 v32, v24 offset:512
	v_xor_b32_e32 v24, 3, v5
	v_lshl_add_u32 v24, v24, 2, s2
	ds_read_b32 v33, v24 offset:768
	v_xor_b32_e32 v24, 4, v5
	v_lshl_add_u32 v24, v24, 2, s2
	ds_read_b32 v34, v24 offset:1024
	v_xor_b32_e32 v24, 5, v5
	v_lshl_add_u32 v24, v24, 2, s2
	ds_read_b32 v35, v24 offset:1280
	v_xor_b32_e32 v24, 6, v5
	v_lshl_add_u32 v24, v24, 2, s2
	ds_read_b32 v36, v24 offset:1536
	v_xor_b32_e32 v24, 7, v5
	v_lshl_add_u32 v24, v24, 2, s2
	ds_read_b32 v37, v24 offset:1792
	v_xor_b32_e32 v24, 8, v5
	v_lshl_add_u32 v24, v24, 2, s2
	ds_read_b32 v38, v24 offset:2048
	v_xor_b32_e32 v24, 9, v5
	v_lshl_add_u32 v24, v24, 2, s2
	ds_read_b32 v39, v24 offset:2304
	v_xor_b32_e32 v24, 10, v5
	v_lshl_add_u32 v24, v24, 2, s2
	ds_read_b32 v40, v24 offset:2560
	v_xor_b32_e32 v24, 11, v5
	v_lshl_add_u32 v24, v24, 2, s2
	ds_read_b32 v41, v24 offset:2816
	v_xor_b32_e32 v24, 12, v5
	v_lshl_add_u32 v24, v24, 2, s2
	ds_read_b32 v42, v24 offset:3072
	v_xor_b32_e32 v24, 13, v5
	v_lshl_add_u32 v24, v24, 2, s2
	ds_read_b32 v43, v24 offset:3328
	v_xor_b32_e32 v24, 14, v5
	v_lshl_add_u32 v24, v24, 2, s2
	ds_read_b32 v44, v24 offset:3584
	v_xor_b32_e32 v24, 15, v5
	v_lshl_add_u32 v24, v24, 2, s2
	ds_read_b32 v45, v24 offset:3840
	v_xor_b32_e32 v24, 16, v5
	v_lshl_add_u32 v24, v24, 2, s2
	ds_read_b32 v46, v24 offset:4096
	v_xor_b32_e32 v24, 17, v5
	v_lshl_add_u32 v24, v24, 2, s2
	ds_read_b32 v47, v24 offset:4352
	v_xor_b32_e32 v24, 18, v5
	v_lshl_add_u32 v24, v24, 2, s2
	ds_read_b32 v48, v24 offset:4608
	v_xor_b32_e32 v24, 19, v5
	v_lshl_add_u32 v24, v24, 2, s2
	ds_read_b32 v49, v24 offset:4864
	v_xor_b32_e32 v24, 20, v5
	v_lshl_add_u32 v24, v24, 2, s2
	ds_read_b32 v50, v24 offset:5120
	v_xor_b32_e32 v24, 21, v5
	v_lshl_add_u32 v24, v24, 2, s2
	ds_read_b32 v51, v24 offset:5376
	v_xor_b32_e32 v24, 22, v5
	v_lshl_add_u32 v24, v24, 2, s2
	ds_read_b32 v52, v24 offset:5632
	v_xor_b32_e32 v24, 23, v5
	v_lshl_add_u32 v24, v24, 2, s2
	ds_read_b32 v53, v24 offset:5888
	v_xor_b32_e32 v24, 24, v5
	v_lshl_add_u32 v24, v24, 2, s2
	ds_read_b32 v54, v24 offset:6144
	v_xor_b32_e32 v24, 25, v5
	v_lshl_add_u32 v24, v24, 2, s2
	ds_read_b32 v55, v24 offset:6400
	v_xor_b32_e32 v24, 26, v5
	v_lshl_add_u32 v24, v24, 2, s2
	ds_read_b32 v56, v24 offset:6656
	v_xor_b32_e32 v24, 27, v5
	v_lshl_add_u32 v24, v24, 2, s2
	ds_read_b32 v57, v24 offset:6912
	v_xor_b32_e32 v24, 28, v5
	v_lshl_add_u32 v24, v24, 2, s2
	ds_read_b32 v58, v24 offset:7168
	v_xor_b32_e32 v24, 29, v5
	v_lshl_add_u32 v24, v24, 2, s2
	ds_read_b32 v59, v24 offset:7424
	v_xor_b32_e32 v24, 30, v5
	v_lshl_add_u32 v24, v24, 2, s2
	ds_read_b32 v60, v24 offset:7680
	v_xor_b32_e32 v24, 31, v5
	v_lshl_add_u32 v24, v24, 2, s2
	ds_read_b32 v61, v24 offset:7936
	s_waitcnt lgkmcnt(0)
	global_store_dword v[22:23], v30, off
	global_store_dword v[22:23], v31, off offset:256
	global_store_dword v[22:23], v32, off offset:512
	global_store_dword v[22:23], v33, off offset:768
	global_store_dword v[22:23], v34, off offset:1024
	global_store_dword v[22:23], v35, off offset:1280
	global_store_dword v[22:23], v36, off offset:1536
	global_store_dword v[22:23], v37, off offset:1792
	global_store_dword v[22:23], v38, off offset:2048
	global_store_dword v[22:23], v39, off offset:2304
	global_store_dword v[22:23], v40, off offset:2560
	global_store_dword v[22:23], v41, off offset:2816
	global_store_dword v[22:23], v42, off offset:3072
	global_store_dword v[22:23], v43, off offset:3328
	global_store_dword v[22:23], v44, off offset:3584
	global_store_dword v[22:23], v45, off offset:3840
	v_lshl_add_u64 v[22:23], v[22:23], 0, s[40:41]
	global_store_dword v[22:23], v46, off
	global_store_dword v[22:23], v47, off offset:256
	global_store_dword v[22:23], v48, off offset:512
	global_store_dword v[22:23], v49, off offset:768
	global_store_dword v[22:23], v50, off offset:1024
	global_store_dword v[22:23], v51, off offset:1280
	global_store_dword v[22:23], v52, off offset:1536
	global_store_dword v[22:23], v53, off offset:1792
	global_store_dword v[22:23], v54, off offset:2048
	global_store_dword v[22:23], v55, off offset:2304
	global_store_dword v[22:23], v56, off offset:2560
	global_store_dword v[22:23], v57, off offset:2816
	global_store_dword v[22:23], v58, off offset:3072
	global_store_dword v[22:23], v59, off offset:3328
	global_store_dword v[22:23], v60, off offset:3584
	global_store_dword v[22:23], v61, off offset:3840
	v_lshl_add_u64 v[22:23], v[22:23], 0, s[40:41]
	s_mov_b64 exec, 0xffff
	global_store_dword v[22:23], v63, off
	s_mov_b64 exec, -1
	s_barrier
	s_branch .LBB0_357
